# ret_u: operand loads fetched one k-step ahead; the 512 second-round units split into 1024 half-units over workgroups 0..127 (critical path 1.5 units instead of 2)
# speedup vs baseline: 1.0074x; 1.0074x over previous
.LBB0_467:
	s_or_b64 exec, exec, s[2:3]
	v_mov_b32_e32 v2, v195
	v_mov_b32_e32 v1, v195
	s_barrier
	v_readlane_b32 s0, v253, 5
	v_ashrrev_i32_e32 v0, 6, v1
	s_movk_i32 s2, 0xa00
	v_lshl_add_u32 v122, s0, 3, v0
	v_cmp_gt_i32_e32 vcc, s2, v122
	s_and_saveexec_b64 s[2:3], vcc
	s_xor_b64 s[2:3], exec, s[2:3]
	s_cbranch_execz .LBB0_475
	v_and_b32_e32 v123, 15, v2
	v_bfe_u32 v1, v1, 6, 2
	v_lshl_or_b32 v125, v1, 6, v123
	v_bfe_u32 v2, v2, 4, 2
	v_lshl_or_b32 v192, s36, 3, v1
	v_mul_u32_u24_e32 v1, 0x14000, v125
	v_lshlrev_b32_e32 v3, 3, v2
	v_lshl_add_u64 v[88:89], v[192:193], 2, s[48:49]
	v_lshlrev_b32_e32 v192, 4, v2
	v_lshlrev_b32_e32 v1, 1, v1
	v_readlane_b32 s4, v253, 1
	v_lshlrev_b32_e32 v124, 8, v2
	v_or_b32_e32 v141, 7, v3
	v_xor_b32_e32 v142, 0x78, v3
	v_or_b32_e32 v2, v1, v192
	v_mov_b32_e32 v3, v193
	v_readlane_b32 s5, v253, 2
	v_lshlrev_b32_e32 v0, 5, v0
	v_or_b32_e32 v126, 0xc00, v124
	v_or_b32_e32 v127, 64, v124
	v_or_b32_e32 v128, 0x80, v124
	v_or_b32_e32 v129, 0xc0, v124
	v_or_b32_e32 v130, 0x400, v124
	v_or_b32_e32 v131, 0x440, v124
	v_or_b32_e32 v132, 0x480, v124
	v_or_b32_e32 v133, 0x4c0, v124
	v_or_b32_e32 v134, 0x800, v124
	v_or_b32_e32 v135, 0x840, v124
	v_or_b32_e32 v136, 0x880, v124
	v_or_b32_e32 v137, 0x8c0, v124
	v_or_b32_e32 v138, 0xc40, v124
	v_or_b32_e32 v139, 0xc80, v124
	v_or_b32_e32 v140, 0xcc0, v124
	v_lshl_add_u64 v[90:91], s[4:5], 0, v[2:3]
	v_lshl_add_u32 v143, s0, 8, v0
	v_lshl_add_u64 v[92:93], s[4:5], 0, v[192:193]
	s_mov_b64 s[4:5], 0
	s_mov_b32 s101, 0
.LBB0_469:
	global_load_dword v2, v[88:89], off
	s_mov_b32 s6, 0xbfb8aa3b
	s_mov_b32 s7, 0x42ce8ed0
	s_mov_b32 s8, 0xc2b17218
	s_mov_b32 s10, 0x3f2aaaab
	s_mov_b32 s12, 0x3f317218
	s_mov_b32 s9, 0x7f800000
	s_mov_b32 s13, 0x33800000
	v_and_b32_e32 v0, 0xffffff80, v143
	v_ashrrev_i32_e32 v1, 31, v0
	v_lshlrev_b64 v[0:1], 1, v[0:1]
	v_lshl_add_u64 v[94:95], v[90:91], 0, v[0:1]
	s_and_b32 s0, s101, 0xff
	v_lshl_add_u64 v[100:101], v[92:93], 0, v[0:1]
	s_waitcnt vmcnt(0)
	v_mul_f32_e32 v3, 0xbfb8aa3b, v2
	v_rndne_f32_e32 v4, v3
	v_sub_f32_e32 v5, v3, v4
	v_fma_f32 v3, v2, s6, -v3
	v_fmac_f32_e32 v3, 0xb2a5705f, v2
	v_add_f32_e32 v3, v5, v3
	v_exp_f32_e32 v3, v3
	v_cvt_i32_f32_e32 v4, v4
	v_cmp_nlt_f32_e32 vcc, s7, v2
	v_ldexp_f32 v3, v3, v4
	s_nop 0
	v_cndmask_b32_e32 v3, 0, v3, vcc
	v_cmp_ngt_f32_e32 vcc, s8, v2
	s_nop 1
	v_cndmask_b32_e32 v4, v224, v3, vcc
	v_add_f32_e32 v5, 1.0, v4
	v_add_f32_e32 v2, -1.0, v5
	v_sub_f32_e32 v3, v2, v5
	v_add_f32_e32 v3, 1.0, v3
	v_sub_f32_e32 v2, v4, v2
	v_add_f32_e32 v6, v2, v3
	v_frexp_mant_f32_e32 v2, v5
	v_cmp_gt_f32_e32 vcc, s10, v2
	v_cvt_f64_f32_e32 v[2:3], v5
	v_frexp_exp_i32_f64_e32 v2, v[2:3]
	v_subbrev_co_u32_e32 v2, vcc, 0, v2, vcc
	v_sub_u32_e32 v3, 0, v2
	v_ldexp_f32 v5, v5, v3
	v_ldexp_f32 v3, v6, v3
	v_add_f32_e32 v6, -1.0, v5
	v_add_f32_e32 v7, 1.0, v6
	v_sub_f32_e32 v7, v5, v7
	v_add_f32_e32 v7, v3, v7
	v_add_f32_e32 v8, v6, v7
	v_sub_f32_e32 v6, v6, v8
	v_add_f32_e32 v6, v7, v6
	v_add_f32_e32 v7, 1.0, v5
	v_add_f32_e32 v9, -1.0, v7
	v_sub_f32_e32 v5, v5, v9
	v_add_f32_e32 v3, v3, v5
	v_add_f32_e32 v5, v7, v3
	v_sub_f32_e32 v7, v7, v5
	v_add_f32_e32 v3, v3, v7
	v_rcp_f32_e32 v7, v5
	v_cvt_f32_i32_e32 v2, v2
	v_cmp_neq_f32_e32 vcc, s9, v4
	v_mul_f32_e32 v9, v8, v7
	v_mul_f32_e32 v10, v5, v9
	v_fma_f32 v11, v9, v5, -v10
	v_fmac_f32_e32 v11, v9, v3
	v_add_f32_e32 v12, v10, v11
	v_sub_f32_e32 v13, v8, v12
	v_sub_f32_e32 v8, v8, v13
	v_sub_f32_e32 v10, v12, v10
	v_sub_f32_e32 v8, v8, v12
	v_add_f32_e32 v6, v6, v8
	v_sub_f32_e32 v8, v10, v11
	v_add_f32_e32 v6, v8, v6
	v_add_f32_e32 v8, v13, v6
	v_mul_f32_e32 v10, v7, v8
	v_mul_f32_e32 v11, v5, v10
	v_fma_f32 v5, v10, v5, -v11
	v_fmac_f32_e32 v5, v10, v3
	v_sub_f32_e32 v3, v13, v8
	v_add_f32_e32 v3, v6, v3
	v_add_f32_e32 v6, v11, v5
	v_sub_f32_e32 v12, v8, v6
	v_sub_f32_e32 v8, v8, v12
	v_sub_f32_e32 v11, v6, v11
	v_sub_f32_e32 v6, v8, v6
	v_add_f32_e32 v3, v3, v6
	v_sub_f32_e32 v5, v11, v5
	v_add_f32_e32 v3, v5, v3
	v_add_f32_e32 v5, v9, v10
	v_add_f32_e32 v3, v12, v3
	v_sub_f32_e32 v6, v5, v9
	v_mul_f32_e32 v3, v7, v3
	v_sub_f32_e32 v6, v10, v6
	v_add_f32_e32 v3, v6, v3
	v_mul_f32_e32 v9, 0x3f317218, v2
	v_add_f32_e32 v6, v5, v3
	v_fma_f32 v10, v2, s12, -v9
	v_mul_f32_e32 v7, v6, v6
	v_fmac_f32_e32 v10, 0xb102e308, v2
	v_sub_f32_e32 v2, v6, v5
	v_fmamk_f32 v8, v7, 0x3e9b6dac, v221
	v_sub_f32_e32 v2, v3, v2
	v_add_f32_e32 v3, v9, v10
	v_fmaak_f32 v8, v7, v8, 0x3f2aaada
	v_sub_f32_e32 v5, v3, v9
	v_ldexp_f32 v9, v6, 1
	v_mul_f32_e32 v6, v6, v7
	v_mul_f32_e32 v6, v6, v8
	v_add_f32_e32 v7, v9, v6
	v_sub_f32_e32 v8, v7, v9
	v_ldexp_f32 v2, v2, 1
	v_sub_f32_e32 v6, v6, v8
	v_add_f32_e32 v2, v2, v6
	v_add_f32_e32 v6, v7, v2
	v_sub_f32_e32 v7, v6, v7
	v_sub_f32_e32 v2, v2, v7
	v_add_f32_e32 v7, v3, v6
	v_sub_f32_e32 v8, v7, v3
	v_sub_f32_e32 v9, v7, v8
	v_sub_f32_e32 v5, v10, v5
	v_sub_f32_e32 v3, v3, v9
	v_sub_f32_e32 v6, v6, v8
	v_add_f32_e32 v3, v6, v3
	v_add_f32_e32 v6, v5, v2
	v_sub_f32_e32 v8, v6, v5
	v_sub_f32_e32 v9, v6, v8
	v_sub_f32_e32 v5, v5, v9
	v_sub_f32_e32 v2, v2, v8
	v_add_f32_e32 v3, v6, v3
	v_add_f32_e32 v2, v2, v5
	v_add_f32_e32 v5, v7, v3
	v_sub_f32_e32 v6, v5, v7
	v_sub_f32_e32 v3, v3, v6
	v_add_f32_e32 v2, v2, v3
	v_add_f32_e32 v2, v5, v2
	v_cndmask_b32_e32 v2, v224, v2, vcc
	v_cmp_lt_f32_e64 vcc, |v4|, s13
	s_nop 1
	v_cndmask_b32_e32 v2, v2, v4, vcc
	v_mul_f32_e32 v144, 0xbfb8aa3b, v2
	global_load_dword v2, v[88:89], off offset:16
	s_waitcnt vmcnt(0)
	v_mul_f32_e32 v3, 0xbfb8aa3b, v2
	v_rndne_f32_e32 v4, v3
	v_sub_f32_e32 v5, v3, v4
	v_fma_f32 v3, v2, s6, -v3
	v_fmac_f32_e32 v3, 0xb2a5705f, v2
	v_add_f32_e32 v3, v5, v3
	v_exp_f32_e32 v3, v3
	v_cvt_i32_f32_e32 v4, v4
	v_cmp_nlt_f32_e32 vcc, s7, v2
	v_readlane_b32 s6, v253, 56
	v_readlane_b32 s7, v253, 57
	v_ldexp_f32 v3, v3, v4
	v_cndmask_b32_e32 v3, 0, v3, vcc
	v_cmp_ngt_f32_e32 vcc, s8, v2
	s_nop 1
	v_cndmask_b32_e32 v2, v224, v3, vcc
	v_add_f32_e32 v3, 1.0, v2
	v_add_f32_e32 v4, -1.0, v3
	v_sub_f32_e32 v5, v4, v3
	v_add_f32_e32 v5, 1.0, v5
	v_sub_f32_e32 v4, v2, v4
	v_add_f32_e32 v6, v4, v5
	v_frexp_mant_f32_e32 v4, v3
	v_cmp_gt_f32_e32 vcc, s10, v4
	v_cvt_f64_f32_e32 v[4:5], v3
	v_frexp_exp_i32_f64_e32 v4, v[4:5]
	v_subbrev_co_u32_e32 v4, vcc, 0, v4, vcc
	v_sub_u32_e32 v5, 0, v4
	v_ldexp_f32 v3, v3, v5
	v_ldexp_f32 v5, v6, v5
	v_add_f32_e32 v6, -1.0, v3
	v_add_f32_e32 v7, 1.0, v6
	v_sub_f32_e32 v7, v3, v7
	v_add_f32_e32 v7, v5, v7
	v_add_f32_e32 v8, v6, v7
	v_sub_f32_e32 v6, v6, v8
	v_add_f32_e32 v6, v7, v6
	v_add_f32_e32 v7, 1.0, v3
	v_add_f32_e32 v9, -1.0, v7
	v_sub_f32_e32 v3, v3, v9
	v_add_f32_e32 v3, v5, v3
	v_add_f32_e32 v5, v7, v3
	v_sub_f32_e32 v7, v7, v5
	v_add_f32_e32 v3, v3, v7
	v_rcp_f32_e32 v7, v5
	v_cvt_f32_i32_e32 v4, v4
	v_cmp_neq_f32_e32 vcc, s9, v2
	s_cmp_eq_u32 s101, 0
	s_cselect_b64 s[8:9], -1, 0
	v_mul_f32_e32 v9, v8, v7
	v_mul_f32_e32 v10, v5, v9
	v_fma_f32 v11, v9, v5, -v10
	v_fmac_f32_e32 v11, v9, v3
	v_add_f32_e32 v12, v10, v11
	v_sub_f32_e32 v13, v8, v12
	v_sub_f32_e32 v8, v8, v13
	v_sub_f32_e32 v10, v12, v10
	v_sub_f32_e32 v8, v8, v12
	v_add_f32_e32 v6, v6, v8
	v_sub_f32_e32 v8, v10, v11
	v_add_f32_e32 v6, v8, v6
	v_add_f32_e32 v8, v13, v6
	v_mul_f32_e32 v10, v7, v8
	v_mul_f32_e32 v11, v5, v10
	v_fma_f32 v5, v10, v5, -v11
	v_fmac_f32_e32 v5, v10, v3
	v_sub_f32_e32 v3, v13, v8
	v_add_f32_e32 v3, v6, v3
	v_add_f32_e32 v6, v11, v5
	v_sub_f32_e32 v12, v8, v6
	v_sub_f32_e32 v8, v8, v12
	v_sub_f32_e32 v11, v6, v11
	v_sub_f32_e32 v6, v8, v6
	v_add_f32_e32 v3, v3, v6
	v_sub_f32_e32 v5, v11, v5
	v_add_f32_e32 v3, v5, v3
	v_add_f32_e32 v5, v9, v10
	v_add_f32_e32 v3, v12, v3
	v_sub_f32_e32 v6, v5, v9
	v_mul_f32_e32 v3, v7, v3
	v_sub_f32_e32 v6, v10, v6
	v_add_f32_e32 v3, v6, v3
	v_mul_f32_e32 v9, 0x3f317218, v4
	v_add_f32_e32 v6, v5, v3
	v_fma_f32 v10, v4, s12, -v9
	v_mul_f32_e32 v7, v6, v6
	v_fmac_f32_e32 v10, 0xb102e308, v4
	v_sub_f32_e32 v4, v6, v5
	v_fmamk_f32 v8, v7, 0x3e9b6dac, v221
	v_sub_f32_e32 v3, v3, v4
	v_add_f32_e32 v4, v9, v10
	v_fmaak_f32 v8, v7, v8, 0x3f2aaada
	v_sub_f32_e32 v5, v4, v9
	v_ldexp_f32 v9, v6, 1
	v_mul_f32_e32 v6, v6, v7
	v_mul_f32_e32 v6, v6, v8
	v_add_f32_e32 v7, v9, v6
	v_sub_f32_e32 v8, v7, v9
	v_ldexp_f32 v3, v3, 1
	v_sub_f32_e32 v6, v6, v8
	v_add_f32_e32 v3, v3, v6
	v_add_f32_e32 v6, v7, v3
	v_sub_f32_e32 v7, v6, v7
	v_sub_f32_e32 v3, v3, v7
	v_add_f32_e32 v7, v4, v6
	v_sub_f32_e32 v8, v7, v4
	v_sub_f32_e32 v9, v7, v8
	v_sub_f32_e32 v5, v10, v5
	v_sub_f32_e32 v4, v4, v9
	v_sub_f32_e32 v6, v6, v8
	v_add_f32_e32 v4, v6, v4
	v_add_f32_e32 v6, v5, v3
	v_sub_f32_e32 v8, v6, v5
	v_sub_f32_e32 v9, v6, v8
	v_sub_f32_e32 v5, v5, v9
	v_sub_f32_e32 v3, v3, v8
	v_add_f32_e32 v4, v6, v4
	v_add_f32_e32 v3, v3, v5
	v_add_f32_e32 v5, v7, v4
	v_sub_f32_e32 v6, v5, v7
	v_sub_f32_e32 v4, v4, v6
	v_add_f32_e32 v3, v3, v4
	v_add_f32_e32 v3, v5, v3
	v_cndmask_b32_e32 v3, v224, v3, vcc
	v_cmp_lt_f32_e64 vcc, |v2|, s13
	s_nop 1
	v_cndmask_b32_e32 v2, v3, v2, vcc
	v_mul_f32_e32 v145, 0xbfb8aa3b, v2
	v_lshlrev_b32_e32 v2, 1, v122
	v_ashrrev_i32_e32 v3, 31, v2
	v_lshlrev_b64 v[4:5], 14, v[2:3]
	v_or_b32_e32 v2, 1, v2
	v_ashrrev_i32_e32 v3, 31, v2
	v_lshlrev_b64 v[2:3], 14, v[2:3]
	v_lshl_add_u64 v[96:97], s[6:7], 0, v[4:5]
	v_lshl_add_u64 v[98:99], s[6:7], 0, v[2:3]
.LBB0_470:
	v_or_b32_e32 v0, s0, v125
	v_mul_u32_u24_e32 v192, 0x14000, v0
	v_mov_b32_e32 v0, 0
	s_xor_b64 s[6:7], s[8:9], -1
	v_lshl_add_u64 v[102:103], v[192:193], 1, v[100:101]
	s_mov_b64 s[8:9], 0
	v_mov_b32_e32 v146, v142
	v_mov_b32_e32 v147, v141
	v_mov_b32_e32 v188, v94
	v_mov_b32_e32 v189, v95
	s_mov_b32 s100, 0x15ed8000
	v_add_co_u32_e32 v190, vcc, s100, v188
	s_nop 1
	v_addc_co_u32_e32 v191, vcc, 0, v189, vcc
	global_load_dwordx4 v[160:163], v[190:191], off
	s_mov_b32 s100, 0x16158000
	v_add_co_u32_e32 v190, vcc, s100, v188
	s_nop 1
	v_addc_co_u32_e32 v191, vcc, 0, v189, vcc
	global_load_dwordx4 v[164:167], v[190:191], off
	s_mov_b32 s100, 0x163d8000
	v_add_co_u32_e32 v190, vcc, s100, v188
	s_nop 1
	v_addc_co_u32_e32 v191, vcc, 0, v189, vcc
	global_load_dwordx4 v[168:171], v[190:191], off
	s_mov_b32 s100, 0x16658000
	v_add_co_u32_e32 v190, vcc, s100, v188
	s_nop 1
	v_addc_co_u32_e32 v191, vcc, 0, v189, vcc
	global_load_dwordx4 v[172:175], v[190:191], off
	v_mov_b32_e32 v188, v102
	v_mov_b32_e32 v189, v103
	s_mov_b32 s100, 0x136d8000
	v_add_co_u32_e32 v190, vcc, s100, v188
	s_nop 1
	v_addc_co_u32_e32 v191, vcc, 0, v189, vcc
	global_load_dwordx4 v[176:179], v[190:191], off
	s_mov_b32 s100, 0x13958000
	v_add_co_u32_e32 v190, vcc, s100, v188
	s_nop 1
	v_addc_co_u32_e32 v191, vcc, 0, v189, vcc
	global_load_dwordx4 v[180:183], v[190:191], off
	v_mov_b32_e32 v1, v0
	v_mov_b32_e32 v2, v0
	v_mov_b32_e32 v3, v0
	v_mov_b32_e32 v8, v0
	v_mov_b32_e32 v9, v0
	v_mov_b32_e32 v10, v0
	v_mov_b32_e32 v11, v0
	v_mov_b32_e32 v16, v0
	v_mov_b32_e32 v17, v0
	v_mov_b32_e32 v18, v0
	v_mov_b32_e32 v19, v0
	v_mov_b32_e32 v24, v0
	v_mov_b32_e32 v25, v0
	v_mov_b32_e32 v26, v0
	v_mov_b32_e32 v27, v0
	v_mov_b32_e32 v32, v0
	v_mov_b32_e32 v33, v0
	v_mov_b32_e32 v34, v0
	v_mov_b32_e32 v35, v0
	v_mov_b32_e32 v40, v0
	v_mov_b32_e32 v41, v0
	v_mov_b32_e32 v42, v0
	v_mov_b32_e32 v43, v0
	v_mov_b32_e32 v48, v0
	v_mov_b32_e32 v49, v0
	v_mov_b32_e32 v50, v0
	v_mov_b32_e32 v51, v0
	v_mov_b32_e32 v52, v0
	v_mov_b32_e32 v53, v0
	v_mov_b32_e32 v54, v0
	v_mov_b32_e32 v55, v0
	v_mov_b32_e32 v4, v0
	v_mov_b32_e32 v5, v0
	v_mov_b32_e32 v6, v0
	v_mov_b32_e32 v7, v0
	v_mov_b32_e32 v12, v0
	v_mov_b32_e32 v13, v0
	v_mov_b32_e32 v14, v0
	v_mov_b32_e32 v15, v0
	v_mov_b32_e32 v20, v0
	v_mov_b32_e32 v21, v0
	v_mov_b32_e32 v22, v0
	v_mov_b32_e32 v23, v0
	v_mov_b32_e32 v28, v0
	v_mov_b32_e32 v29, v0
	v_mov_b32_e32 v30, v0
	v_mov_b32_e32 v31, v0
	v_mov_b32_e32 v36, v0
	v_mov_b32_e32 v37, v0
	v_mov_b32_e32 v38, v0
	v_mov_b32_e32 v39, v0
	v_mov_b32_e32 v44, v0
	v_mov_b32_e32 v45, v0
	v_mov_b32_e32 v46, v0
	v_mov_b32_e32 v47, v0
	v_mov_b32_e32 v56, v0
	v_mov_b32_e32 v57, v0
	v_mov_b32_e32 v58, v0
	v_mov_b32_e32 v59, v0
	v_mov_b32_e32 v60, v0
	v_mov_b32_e32 v61, v0
	v_mov_b32_e32 v62, v0
	v_mov_b32_e32 v63, v0
.LBB0_471:
	s_waitcnt vmcnt(0)
	v_mov_b32_e32 v64, v160
	v_mov_b32_e32 v65, v161
	v_mov_b32_e32 v66, v162
	v_mov_b32_e32 v67, v163
	v_mov_b32_e32 v68, v164
	v_mov_b32_e32 v69, v165
	v_mov_b32_e32 v70, v166
	v_mov_b32_e32 v71, v167
	v_mov_b32_e32 v72, v168
	v_mov_b32_e32 v73, v169
	v_mov_b32_e32 v74, v170
	v_mov_b32_e32 v75, v171
	v_mov_b32_e32 v76, v172
	v_mov_b32_e32 v77, v173
	v_mov_b32_e32 v78, v174
	v_mov_b32_e32 v79, v175
	v_mov_b32_e32 v80, v176
	v_mov_b32_e32 v81, v177
	v_mov_b32_e32 v82, v178
	v_mov_b32_e32 v83, v179
	v_mov_b32_e32 v184, v180
	v_mov_b32_e32 v185, v181
	v_mov_b32_e32 v186, v182
	v_mov_b32_e32 v187, v183
	s_cmpk_eq_i32 s8, 0xc0
	s_cbranch_scc1 .Lru_nopf
	s_add_u32 s98, s8, 64
	s_addc_u32 s99, s9, 0
	v_lshl_add_u64 v[188:189], v[94:95], 0, s[98:99]
	s_mov_b32 s100, 0x15ed8000
	v_add_co_u32_e32 v190, vcc, s100, v188
	s_nop 1
	v_addc_co_u32_e32 v191, vcc, 0, v189, vcc
	global_load_dwordx4 v[160:163], v[190:191], off
	s_mov_b32 s100, 0x16158000
	v_add_co_u32_e32 v190, vcc, s100, v188
	s_nop 1
	v_addc_co_u32_e32 v191, vcc, 0, v189, vcc
	global_load_dwordx4 v[164:167], v[190:191], off
	s_mov_b32 s100, 0x163d8000
	v_add_co_u32_e32 v190, vcc, s100, v188
	s_nop 1
	v_addc_co_u32_e32 v191, vcc, 0, v189, vcc
	global_load_dwordx4 v[168:171], v[190:191], off
	s_mov_b32 s100, 0x16658000
	v_add_co_u32_e32 v190, vcc, s100, v188
	s_nop 1
	v_addc_co_u32_e32 v191, vcc, 0, v189, vcc
	global_load_dwordx4 v[172:175], v[190:191], off
	v_lshl_add_u64 v[188:189], v[102:103], 0, s[98:99]
	s_mov_b32 s100, 0x136d8000
	v_add_co_u32_e32 v190, vcc, s100, v188
	s_nop 1
	v_addc_co_u32_e32 v191, vcc, 0, v189, vcc
	global_load_dwordx4 v[176:179], v[190:191], off
	s_mov_b32 s100, 0x13958000
	v_add_co_u32_e32 v190, vcc, s100, v188
	s_nop 1
	v_addc_co_u32_e32 v191, vcc, 0, v189, vcc
	global_load_dwordx4 v[180:183], v[190:191], off
.Lru_nopf:
	s_mov_b32 s10, 0x15ed8000
	s_mov_b32 s10, 0x16158000
	s_nop 0
	s_mov_b32 s10, 0x163d8000
	s_nop 0
	s_mov_b32 s10, 0x16658000
	s_nop 0
	v_lshl_add_u64 v[120:121], v[102:103], 0, s[8:9]
	s_nop 0
	s_mov_b32 s10, 0x136d8000
	v_add_u32_e32 v85, 7, v146
	s_nop 0
	v_cvt_f32_u32_e32 v85, v85
	v_add_u32_e32 v84, -7, v147
	v_cvt_f32_u32_e32 v84, v84
	v_mul_f32_e32 v86, v144, v85
	v_cmp_gt_f32_e32 vcc, s96, v86
	s_mov_b32 s10, 0x13958000
	v_cndmask_b32_e32 v86, 0, v225, vcc
	v_fmac_f32_e32 v86, v144, v85
	v_exp_f32_e32 v85, v86
	v_cndmask_b32_e32 v86, 0, v226, vcc
	s_add_u32 s8, s8, 64
	v_ldexp_f32 v104, v85, v86
	v_add_u32_e32 v85, 6, v146
	v_cvt_f32_u32_e32 v85, v85
	s_addc_u32 s9, s9, 0
	s_cmpk_eq_i32 s8, 0x100
	v_mul_f32_e32 v86, v144, v85
	v_cmp_gt_f32_e32 vcc, s96, v86
	s_nop 0
	v_and_b32_e32 v149, 0xffff0000, v83
	v_cndmask_b32_e32 v86, 0, v225, vcc
	v_fmac_f32_e32 v86, v144, v85
	v_exp_f32_e32 v85, v86
	v_cndmask_b32_e32 v86, 0, v226, vcc
	v_ldexp_f32 v105, v85, v86
	v_mul_f32_e32 v85, v145, v84
	v_cmp_gt_f32_e32 vcc, s96, v85
	s_nop 1
	v_cndmask_b32_e32 v85, 0, v225, vcc
	v_fmac_f32_e32 v85, v145, v84
	v_exp_f32_e32 v84, v85
	v_cndmask_b32_e32 v85, 0, v226, vcc
	v_ldexp_f32 v106, v84, v85
	v_add_u32_e32 v84, -6, v147
	v_cvt_f32_u32_e32 v84, v84
	v_mul_f32_e32 v85, v145, v84
	v_cmp_gt_f32_e32 vcc, s96, v85
	s_nop 1
	v_cndmask_b32_e32 v85, 0, v225, vcc
	v_fmac_f32_e32 v85, v145, v84
	v_exp_f32_e32 v84, v85
	v_cndmask_b32_e32 v85, 0, v226, vcc
	v_ldexp_f32 v107, v84, v85
	v_lshlrev_b32_e32 v84, 16, v80
	v_and_b32_e32 v85, 0xffff0000, v80
	v_pk_mul_f32 v[86:87], v[104:105], v[84:85]
	v_pk_mul_f32 v[84:85], v[106:107], v[84:85]
	v_cvt_pk_bf16_f32 v80, v86, v87
	v_add_u32_e32 v86, 5, v146
	v_cvt_f32_u32_e32 v86, v86
	v_cvt_pk_bf16_f32 v84, v84, v85
	v_add_u32_e32 v85, -5, v147
	v_cvt_f32_u32_e32 v85, v85
	v_mul_f32_e32 v87, v144, v86
	v_cmp_gt_f32_e32 vcc, s96, v87
	s_nop 1
	v_cndmask_b32_e32 v87, 0, v225, vcc
	v_fmac_f32_e32 v87, v144, v86
	v_exp_f32_e32 v86, v87
	v_cndmask_b32_e32 v87, 0, v226, vcc
	v_ldexp_f32 v108, v86, v87
	v_add_u32_e32 v86, 4, v146
	v_cvt_f32_u32_e32 v86, v86
	v_mul_f32_e32 v87, v144, v86
	v_cmp_gt_f32_e32 vcc, s96, v87
	s_nop 1
	v_cndmask_b32_e32 v87, 0, v225, vcc
	v_fmac_f32_e32 v87, v144, v86
	v_exp_f32_e32 v86, v87
	v_cndmask_b32_e32 v87, 0, v226, vcc
	v_ldexp_f32 v109, v86, v87
	v_mul_f32_e32 v86, v145, v85
	v_cmp_gt_f32_e32 vcc, s96, v86
	v_and_b32_e32 v87, 0xffff0000, v81
	s_nop 0
	v_cndmask_b32_e32 v86, 0, v225, vcc
	v_fmac_f32_e32 v86, v145, v85
	v_exp_f32_e32 v85, v86
	v_cndmask_b32_e32 v86, 0, v226, vcc
	v_ldexp_f32 v110, v85, v86
	v_add_u32_e32 v85, -4, v147
	v_cvt_f32_u32_e32 v85, v85
	v_mul_f32_e32 v86, v145, v85
	v_cmp_gt_f32_e32 vcc, s96, v86
	s_nop 1
	v_cndmask_b32_e32 v86, 0, v225, vcc
	v_fmac_f32_e32 v86, v145, v85
	v_exp_f32_e32 v85, v86
	v_cndmask_b32_e32 v86, 0, v226, vcc
	v_ldexp_f32 v111, v85, v86
	v_lshlrev_b32_e32 v86, 16, v81
	v_pk_mul_f32 v[112:113], v[108:109], v[86:87]
	v_pk_mul_f32 v[86:87], v[110:111], v[86:87]
	v_cvt_pk_bf16_f32 v81, v112, v113
	v_cvt_pk_bf16_f32 v85, v86, v87
	v_add_u32_e32 v87, 3, v146
	v_cvt_f32_u32_e32 v87, v87
	v_add_u32_e32 v86, -3, v147
	v_cvt_f32_u32_e32 v86, v86
	v_mul_f32_e32 v112, v144, v87
	v_cmp_gt_f32_e32 vcc, s96, v112
	s_nop 1
	v_cndmask_b32_e32 v112, 0, v225, vcc
	v_fmac_f32_e32 v112, v144, v87
	v_exp_f32_e32 v87, v112
	v_cndmask_b32_e32 v112, 0, v226, vcc
	v_ldexp_f32 v112, v87, v112
	v_add_u32_e32 v87, 2, v146
	v_cvt_f32_u32_e32 v87, v87
	v_mul_f32_e32 v113, v144, v87
	v_cmp_gt_f32_e32 vcc, s96, v113
	s_nop 1
	v_cndmask_b32_e32 v113, 0, v225, vcc
	v_fmac_f32_e32 v113, v144, v87
	v_exp_f32_e32 v87, v113
	v_cndmask_b32_e32 v113, 0, v226, vcc
	v_ldexp_f32 v113, v87, v113
	v_mul_f32_e32 v87, v145, v86
	v_cmp_gt_f32_e32 vcc, s96, v87
	s_nop 1
	v_cndmask_b32_e32 v87, 0, v225, vcc
	v_fmac_f32_e32 v87, v145, v86
	v_exp_f32_e32 v86, v87
	v_cndmask_b32_e32 v87, 0, v226, vcc
	v_ldexp_f32 v114, v86, v87
	v_add_u32_e32 v86, -2, v147
	v_cvt_f32_u32_e32 v86, v86
	v_mul_f32_e32 v87, v145, v86
	v_cmp_gt_f32_e32 vcc, s96, v87
	s_nop 1
	v_cndmask_b32_e32 v87, 0, v225, vcc
	v_fmac_f32_e32 v87, v145, v86
	v_exp_f32_e32 v86, v87
	v_cndmask_b32_e32 v87, 0, v226, vcc
	v_ldexp_f32 v115, v86, v87
	v_lshlrev_b32_e32 v86, 16, v82
	v_and_b32_e32 v87, 0xffff0000, v82
	v_pk_mul_f32 v[116:117], v[112:113], v[86:87]
	v_pk_mul_f32 v[86:87], v[114:115], v[86:87]
	v_cvt_pk_bf16_f32 v82, v116, v117
	v_add_u32_e32 v116, 1, v146
	v_cvt_f32_u32_e32 v116, v116
	v_cvt_pk_bf16_f32 v86, v86, v87
	v_add_u32_e32 v87, -1, v147
	v_cvt_f32_u32_e32 v87, v87
	v_mul_f32_e32 v117, v144, v116
	v_cmp_gt_f32_e32 vcc, s96, v117
	s_nop 1
	v_cndmask_b32_e32 v117, 0, v225, vcc
	v_fmac_f32_e32 v117, v144, v116
	v_exp_f32_e32 v116, v117
	v_cndmask_b32_e32 v117, 0, v226, vcc
	v_ldexp_f32 v116, v116, v117
	v_cvt_f32_u32_e32 v117, v146
	v_subrev_u32_e32 v146, 32, v146
	v_mul_f32_e32 v118, v144, v117
	v_cmp_gt_f32_e32 vcc, s96, v118
	s_nop 1
	v_cndmask_b32_e32 v119, 0, v225, vcc
	v_fmac_f32_e32 v119, v144, v117
	v_exp_f32_e32 v117, v119
	v_cndmask_b32_e32 v118, 0, v226, vcc
	v_ldexp_f32 v117, v117, v118
	v_mul_f32_e32 v118, v145, v87
	v_cmp_gt_f32_e32 vcc, s96, v118
	s_nop 1
	v_cndmask_b32_e32 v118, 0, v225, vcc
	v_fmac_f32_e32 v118, v145, v87
	v_exp_f32_e32 v87, v118
	v_cndmask_b32_e32 v118, 0, v226, vcc
	v_ldexp_f32 v118, v87, v118
	v_cvt_f32_u32_e32 v87, v147
	v_add_u32_e32 v147, 32, v147
	v_mul_f32_e32 v119, v145, v87
	v_cmp_gt_f32_e32 vcc, s96, v119
	s_nop 1
	v_cndmask_b32_e32 v148, 0, v225, vcc
	v_fmac_f32_e32 v148, v145, v87
	v_exp_f32_e32 v87, v148
	v_lshlrev_b32_e32 v148, 16, v83
	v_pk_mul_f32 v[150:151], v[116:117], v[148:149]
	v_cndmask_b32_e32 v119, 0, v226, vcc
	v_cvt_pk_bf16_f32 v83, v150, v151
	v_ldexp_f32 v119, v87, v119
	v_pk_mul_f32 v[148:149], v[118:119], v[148:149]
	s_nop 0
	v_mfma_f32_16x16x32_bf16 v[52:55], v[64:67], v[80:83], v[52:55]
	v_cvt_pk_bf16_f32 v87, v148, v149
	s_nop 0
	v_mfma_f32_16x16x32_bf16 v[40:43], v[68:71], v[80:83], v[40:43]
	s_nop 0
	v_mfma_f32_16x16x32_bf16 v[24:27], v[72:75], v[80:83], v[24:27]
	s_nop 0
	v_mfma_f32_16x16x32_bf16 v[8:11], v[76:79], v[80:83], v[8:11]
	v_add_co_u32_e32 v80, vcc, s10, v120
	s_nop 1
	v_addc_co_u32_e32 v81, vcc, 0, v121, vcc
	v_mov_b32_e32 v80, v184
	v_mov_b32_e32 v81, v185
	v_mov_b32_e32 v82, v186
	v_mov_b32_e32 v83, v187
	v_mfma_f32_16x16x32_bf16 v[60:63], v[64:67], v[84:87], v[60:63]
	v_mfma_f32_16x16x32_bf16 v[44:47], v[68:71], v[84:87], v[44:47]
	v_mfma_f32_16x16x32_bf16 v[28:31], v[72:75], v[84:87], v[28:31]
	v_mfma_f32_16x16x32_bf16 v[12:15], v[76:79], v[84:87], v[12:15]
	s_nop 0
	v_lshlrev_b32_e32 v84, 16, v80
	v_and_b32_e32 v85, 0xffff0000, v80
	v_pk_mul_f32 v[86:87], v[104:105], v[84:85]
	v_pk_mul_f32 v[84:85], v[106:107], v[84:85]
	v_cvt_pk_bf16_f32 v80, v86, v87
	v_lshlrev_b32_e32 v86, 16, v81
	v_and_b32_e32 v87, 0xffff0000, v81
	v_pk_mul_f32 v[104:105], v[108:109], v[86:87]
	v_pk_mul_f32 v[86:87], v[110:111], v[86:87]
	v_cvt_pk_bf16_f32 v84, v84, v85
	v_cvt_pk_bf16_f32 v85, v86, v87
	v_lshlrev_b32_e32 v86, 16, v82
	v_and_b32_e32 v87, 0xffff0000, v82
	v_cvt_pk_bf16_f32 v81, v104, v105
	v_pk_mul_f32 v[104:105], v[112:113], v[86:87]
	v_pk_mul_f32 v[86:87], v[114:115], v[86:87]
	v_cvt_pk_bf16_f32 v82, v104, v105
	v_lshlrev_b32_e32 v104, 16, v83
	v_and_b32_e32 v105, 0xffff0000, v83
	v_pk_mul_f32 v[106:107], v[116:117], v[104:105]
	v_pk_mul_f32 v[104:105], v[118:119], v[104:105]
	v_cvt_pk_bf16_f32 v86, v86, v87
	v_cvt_pk_bf16_f32 v83, v106, v107
	v_cvt_pk_bf16_f32 v87, v104, v105
	s_nop 0
	v_mfma_f32_16x16x32_bf16 v[48:51], v[64:67], v[80:83], v[48:51]
	v_mfma_f32_16x16x32_bf16 v[56:59], v[64:67], v[84:87], v[56:59]
	v_mfma_f32_16x16x32_bf16 v[32:35], v[68:71], v[80:83], v[32:35]
	v_mfma_f32_16x16x32_bf16 v[36:39], v[68:71], v[84:87], v[36:39]
	v_mfma_f32_16x16x32_bf16 v[16:19], v[72:75], v[80:83], v[16:19]
	v_mfma_f32_16x16x32_bf16 v[20:23], v[72:75], v[84:87], v[20:23]
	v_mfma_f32_16x16x32_bf16 v[0:3], v[76:79], v[80:83], v[0:3]
	v_mfma_f32_16x16x32_bf16 v[4:7], v[76:79], v[84:87], v[4:7]
	s_cbranch_scc0 .LBB0_471
	v_or_b32_e32 v68, s0, v123
	v_or_b32_e32 v192, v68, v124
	v_lshlrev_b64 v[64:65], 2, v[192:193]
	v_lshl_add_u64 v[66:67], v[96:97], 0, v[64:65]
	v_lshl_add_u64 v[64:65], v[98:99], 0, v[64:65]
	v_add_u32_e32 v192, v68, v124
	global_store_dword v[64:65], v60, off
	v_lshlrev_b64 v[64:65], 2, v[192:193]
	global_store_dword v[66:67], v52, off
	v_lshl_add_u64 v[66:67], v[96:97], 0, v[64:65]
	global_store_dword v[66:67], v53, off offset:256
	v_lshl_add_u64 v[52:53], v[98:99], 0, v[64:65]
	v_add_u32_e32 v192, v68, v127
	global_store_dword v[52:53], v61, off offset:256
	global_store_dword v[66:67], v54, off offset:512
	global_store_dword v[52:53], v62, off offset:512
	global_store_dword v[66:67], v55, off offset:768
	global_store_dword v[52:53], v63, off offset:768
	global_store_dword v[66:67], v48, off offset:64
	global_store_dword v[52:53], v56, off offset:64
	v_lshlrev_b64 v[52:53], 2, v[192:193]
	v_lshl_add_u64 v[54:55], v[96:97], 0, v[52:53]
	global_store_dword v[54:55], v49, off offset:64
	v_lshl_add_u64 v[48:49], v[98:99], 0, v[52:53]
	v_add_u32_e32 v192, v68, v128
	global_store_dword v[48:49], v57, off offset:64
	v_lshlrev_b64 v[48:49], 2, v[192:193]
	v_lshl_add_u64 v[52:53], v[96:97], 0, v[48:49]
	v_lshl_add_u64 v[48:49], v[98:99], 0, v[48:49]
	v_add_u32_e32 v192, v68, v129
	global_store_dword v[48:49], v58, off offset:64
	v_lshlrev_b64 v[48:49], 2, v[192:193]
	global_store_dword v[52:53], v50, off offset:64
	v_lshl_add_u64 v[52:53], v[96:97], 0, v[48:49]
	v_lshl_add_u64 v[48:49], v[98:99], 0, v[48:49]
	v_or_b32_e32 v192, v68, v130
	global_store_dword v[48:49], v59, off offset:64
	v_lshlrev_b64 v[48:49], 2, v[192:193]
	global_store_dword v[52:53], v51, off offset:64
	v_lshl_add_u64 v[50:51], v[96:97], 0, v[48:49]
	v_lshl_add_u64 v[48:49], v[98:99], 0, v[48:49]
	v_or_b32_e32 v192, v68, v131
	global_store_dword v[48:49], v44, off
	v_lshlrev_b64 v[48:49], 2, v[192:193]
	global_store_dword v[50:51], v40, off
	v_lshl_add_u64 v[50:51], v[96:97], 0, v[48:49]
	global_store_dword v[50:51], v41, off
	v_lshl_add_u64 v[40:41], v[98:99], 0, v[48:49]
	v_or_b32_e32 v192, v68, v132
	global_store_dword v[40:41], v45, off
	v_lshlrev_b64 v[40:41], 2, v[192:193]
	v_lshl_add_u64 v[44:45], v[96:97], 0, v[40:41]
	v_lshl_add_u64 v[40:41], v[98:99], 0, v[40:41]
	v_or_b32_e32 v192, v68, v133
	global_store_dword v[40:41], v46, off
	v_lshlrev_b64 v[40:41], 2, v[192:193]
	global_store_dword v[44:45], v42, off
	v_lshl_add_u64 v[44:45], v[96:97], 0, v[40:41]
	v_lshl_add_u64 v[40:41], v[98:99], 0, v[40:41]
	v_add_u32_e32 v192, v68, v130
	global_store_dword v[40:41], v47, off
	v_lshlrev_b64 v[40:41], 2, v[192:193]
	global_store_dword v[44:45], v43, off
	v_lshl_add_u64 v[42:43], v[96:97], 0, v[40:41]
	v_lshl_add_u64 v[40:41], v[98:99], 0, v[40:41]
	v_add_u32_e32 v192, v68, v131
	global_store_dword v[40:41], v36, off offset:64
	v_lshlrev_b64 v[40:41], 2, v[192:193]
	global_store_dword v[42:43], v32, off offset:64
	v_lshl_add_u64 v[42:43], v[96:97], 0, v[40:41]
	global_store_dword v[42:43], v33, off offset:64
	v_lshl_add_u64 v[32:33], v[98:99], 0, v[40:41]
	v_add_u32_e32 v192, v68, v132
	global_store_dword v[32:33], v37, off offset:64
	v_lshlrev_b64 v[32:33], 2, v[192:193]
	v_lshl_add_u64 v[36:37], v[96:97], 0, v[32:33]
	v_lshl_add_u64 v[32:33], v[98:99], 0, v[32:33]
	v_add_u32_e32 v192, v68, v133
	global_store_dword v[32:33], v38, off offset:64
	v_lshlrev_b64 v[32:33], 2, v[192:193]
	global_store_dword v[36:37], v34, off offset:64
	v_lshl_add_u64 v[36:37], v[96:97], 0, v[32:33]
	v_lshl_add_u64 v[32:33], v[98:99], 0, v[32:33]
	v_or_b32_e32 v192, v68, v134
	global_store_dword v[32:33], v39, off offset:64
	v_lshlrev_b64 v[32:33], 2, v[192:193]
	global_store_dword v[36:37], v35, off offset:64
	v_lshl_add_u64 v[34:35], v[96:97], 0, v[32:33]
	v_lshl_add_u64 v[32:33], v[98:99], 0, v[32:33]
	v_or_b32_e32 v192, v68, v135
	global_store_dword v[32:33], v28, off
	v_lshlrev_b64 v[32:33], 2, v[192:193]
	global_store_dword v[34:35], v24, off
	v_lshl_add_u64 v[34:35], v[96:97], 0, v[32:33]
	global_store_dword v[34:35], v25, off
	v_lshl_add_u64 v[24:25], v[98:99], 0, v[32:33]
	v_or_b32_e32 v192, v68, v136
	global_store_dword v[24:25], v29, off
	v_lshlrev_b64 v[24:25], 2, v[192:193]
	v_lshl_add_u64 v[28:29], v[96:97], 0, v[24:25]
	v_lshl_add_u64 v[24:25], v[98:99], 0, v[24:25]
	v_or_b32_e32 v192, v68, v137
	global_store_dword v[24:25], v30, off
	v_lshlrev_b64 v[24:25], 2, v[192:193]
	global_store_dword v[28:29], v26, off
	v_lshl_add_u64 v[28:29], v[96:97], 0, v[24:25]
	v_lshl_add_u64 v[24:25], v[98:99], 0, v[24:25]
	v_add_u32_e32 v192, v68, v134
	global_store_dword v[24:25], v31, off
	v_lshlrev_b64 v[24:25], 2, v[192:193]
	global_store_dword v[28:29], v27, off
	v_lshl_add_u64 v[26:27], v[96:97], 0, v[24:25]
	v_lshl_add_u64 v[24:25], v[98:99], 0, v[24:25]
	v_add_u32_e32 v192, v68, v135
	global_store_dword v[24:25], v20, off offset:64
	v_lshlrev_b64 v[24:25], 2, v[192:193]
	global_store_dword v[26:27], v16, off offset:64
	v_lshl_add_u64 v[26:27], v[96:97], 0, v[24:25]
	global_store_dword v[26:27], v17, off offset:64
	v_lshl_add_u64 v[16:17], v[98:99], 0, v[24:25]
	v_add_u32_e32 v192, v68, v136
	global_store_dword v[16:17], v21, off offset:64
	v_lshlrev_b64 v[16:17], 2, v[192:193]
	v_lshl_add_u64 v[20:21], v[96:97], 0, v[16:17]
	v_lshl_add_u64 v[16:17], v[98:99], 0, v[16:17]
	v_add_u32_e32 v192, v68, v137
	global_store_dword v[16:17], v22, off offset:64
	v_lshlrev_b64 v[16:17], 2, v[192:193]
	global_store_dword v[20:21], v18, off offset:64
	v_lshl_add_u64 v[20:21], v[96:97], 0, v[16:17]
	v_lshl_add_u64 v[16:17], v[98:99], 0, v[16:17]
	v_or_b32_e32 v192, v68, v126
	global_store_dword v[16:17], v23, off offset:64
	v_lshlrev_b64 v[16:17], 2, v[192:193]
	global_store_dword v[20:21], v19, off offset:64
	v_lshl_add_u64 v[18:19], v[96:97], 0, v[16:17]
	v_lshl_add_u64 v[16:17], v[98:99], 0, v[16:17]
	v_or_b32_e32 v192, v68, v138
	global_store_dword v[16:17], v12, off
	v_lshlrev_b64 v[16:17], 2, v[192:193]
	global_store_dword v[18:19], v8, off
	v_lshl_add_u64 v[18:19], v[96:97], 0, v[16:17]
	global_store_dword v[18:19], v9, off
	v_lshl_add_u64 v[8:9], v[98:99], 0, v[16:17]
	v_or_b32_e32 v192, v68, v139
	global_store_dword v[8:9], v13, off
	v_lshlrev_b64 v[8:9], 2, v[192:193]
	v_lshl_add_u64 v[12:13], v[96:97], 0, v[8:9]
	v_lshl_add_u64 v[8:9], v[98:99], 0, v[8:9]
	v_or_b32_e32 v192, v68, v140
	global_store_dword v[8:9], v14, off
	v_lshlrev_b64 v[8:9], 2, v[192:193]
	global_store_dword v[12:13], v10, off
	v_lshl_add_u64 v[12:13], v[96:97], 0, v[8:9]
	v_lshl_add_u64 v[8:9], v[98:99], 0, v[8:9]
	v_add_u32_e32 v192, v68, v126
	global_store_dword v[8:9], v15, off
	v_lshlrev_b64 v[8:9], 2, v[192:193]
	global_store_dword v[12:13], v11, off
	v_lshl_add_u64 v[10:11], v[96:97], 0, v[8:9]
	v_lshl_add_u64 v[8:9], v[98:99], 0, v[8:9]
	v_add_u32_e32 v192, v68, v138
	global_store_dword v[8:9], v4, off offset:64
	v_lshlrev_b64 v[8:9], 2, v[192:193]
	global_store_dword v[10:11], v0, off offset:64
	v_lshl_add_u64 v[10:11], v[96:97], 0, v[8:9]
	global_store_dword v[10:11], v1, off offset:64
	v_lshl_add_u64 v[0:1], v[98:99], 0, v[8:9]
	v_add_u32_e32 v192, v68, v139
	global_store_dword v[0:1], v5, off offset:64
	v_lshlrev_b64 v[0:1], 2, v[192:193]
	v_lshl_add_u64 v[4:5], v[96:97], 0, v[0:1]
	v_lshl_add_u64 v[0:1], v[98:99], 0, v[0:1]
	v_add_u32_e32 v192, v68, v140
	global_store_dword v[0:1], v6, off offset:64
	v_lshlrev_b64 v[0:1], 2, v[192:193]
	global_store_dword v[4:5], v2, off offset:64
	v_lshl_add_u64 v[4:5], v[96:97], 0, v[0:1]
	v_lshl_add_u64 v[0:1], v[98:99], 0, v[0:1]
	s_mov_b32 s0, 32
	s_mov_b64 s[8:9], 0
	s_and_b64 vcc, exec, s[6:7]
	global_store_dword v[4:5], v3, off offset:64
	global_store_dword v[0:1], v7, off offset:64
	s_cbranch_vccz .LBB0_470
	s_cmp_lg_u32 s101, 0
	s_cbranch_scc1 .Lru_done
	v_readlane_b32 s0, v253, 5
	v_readfirstlane_b32 s98, v195
	s_nop 1
	s_lshr_b32 s98, s98, 6
	s_cmp_lt_u32 s0, 0x80
	s_cbranch_scc0 .Lru_done
	s_and_b32 s99, s98, 3
	s_lshl_b32 s0, s0, 2
	s_add_i32 s0, s0, s99
	s_addk_i32 s0, 0x800
	v_mov_b32_e32 v122, s0
	s_lshl_b32 s0, s0, 5
	v_mov_b32_e32 v143, s0
	s_lshr_b32 s98, s98, 2
	s_and_b32 s98, s98, 1
	s_lshl_b32 s98, s98, 5
	s_or_b32 s101, s98, 0x100
	s_branch .LBB0_469
.Lru_done:
	s_or_b64 exec, exec, s[4:5]
.LBB0_475:
	s_or_b64 exec, exec, s[2:3]
	s_lshl_b32 s0, s36, 5
	s_lshl_b64 s[2:3], s[0:1], 2
	v_readlane_b32 s4, v253, 3
	s_waitcnt vmcnt(0)
	v_readlane_b32 s5, v253, 4
	s_add_u32 s38, s4, s2
	s_addc_u32 s39, s5, s3
	s_waitcnt vmcnt(63) expcnt(7) lgkmcnt(15)
	s_barrier
	s_mov_b64 s[2:3], exec
	v_readlane_b32 s4, v254, 32
	v_readlane_b32 s5, v254, 33
	s_and_b64 s[4:5], s[2:3], s[4:5]
	s_mov_b64 exec, s[4:5]
	s_cbranch_execz .LBB0_478
	s_mov_b64 s[4:5], exec
	v_mbcnt_lo_u32_b32 v0, s4, 0
	buffer_wbl2 sc1
	s_waitcnt vmcnt(0)
	s_waitcnt vmcnt(0)
	v_mbcnt_hi_u32_b32 v0, s5, v0
	v_cmp_eq_u32_e32 vcc, 0, v0
	s_and_b64 s[6:7], exec, vcc
	s_mov_b64 exec, s[6:7]
	s_cbranch_execz .LBB0_478
	s_bcnt1_i32_b64 s0, s[4:5]
	v_mov_b32_e32 v0, s0
	global_atomic_add v193, v0, s[38:39] offset:64
